# scan: consumer waves at s_setprio 3 (producers stay at 2)
# baseline (speedup 1.0000x reference)
; __device__ __forceinline__ void scan_unit_mfma(const TI ti, CArgs& a, int l, int u, bool ctx_out, unsigned char* ldsg) {
;     ...
;     if (w < 2) {
;         const int it = w, r = lane & 31, h = lane >> 5;
;         bf16_t* Y = (bf16_t*)(a.ws + (d ? WS_Y1 : WS_H));
;         f32x16 ST0, ST1;
; #pragma unroll
;         for (int i = 0; i < 16; ++i) { ST0[i] = 0.f; ST1[i] = 0.f; }
;         for (int n = 0; n < NCH + RING; ++n) {
.LBB0_319:
	s_and_b64 vcc, exec, s[4:5]
	s_cbranch_vccz .LBB0_303
	s_cmp_eq_u32 s18, 0
	s_cselect_b64 s[60:61], -1, 0
	s_and_b64 s[4:5], s[60:61], exec
	s_load_dwordx2 s[4:5], s[74:75], 0x110
	s_mov_b32 s1, 0x3200000
	s_cselect_b32 s1, s1, 0x29e00000
	v_mov_b32_e32 v14, v1
	v_mov_b32_e32 v15, v1
	s_waitcnt lgkmcnt(0)
	s_add_u32 s1, s4, s1
	s_addc_u32 s3, s5, 0
	s_lshl_b32 s4, s17, 5
	s_lshl_b32 s7, s16, 11
	s_lshl_b32 s16, s16, 8
	s_addk_i32 s16, 0x4000
	s_ashr_i32 s5, s4, 31
	s_lshl_b32 s10, s14, 7
	s_add_u32 s1, s1, s10
	s_waitcnt vmcnt(0)
	v_or_b32_e32 v0, s4, v80
	s_addc_u32 s3, s3, 0
	s_lshl_b64 s[4:5], s[4:5], 1
	s_add_u32 s4, s1, s4
	v_mul_lo_u32 v98, v0, 48
	s_addc_u32 s5, s3, s5
	v_lshlrev_b32_e32 v0, 1, v80
	v_lshl_add_u64 v[82:83], s[4:5], 0, v[0:1]
	v_mov_b32_e32 v0, v1
	v_mov_b32_e32 v2, v1
	v_mov_b32_e32 v3, v1
	v_mov_b32_e32 v4, v1
	v_mov_b32_e32 v5, v1
	v_mov_b32_e32 v6, v1
	v_mov_b32_e32 v7, v1
	v_mov_b32_e32 v8, v1
	v_mov_b32_e32 v9, v1
	v_mov_b32_e32 v10, v1
	v_mov_b32_e32 v11, v1
	v_mov_b32_e32 v12, v1
	v_mov_b32_e32 v13, v1
	v_mov_b64_e32 v[30:31], v[14:15]
	v_mov_b64_e32 v[46:47], v[14:15]
	s_mov_b32 s6, 0
	s_movk_i32 s14, 0xffea
	v_mov_b64_e32 v[28:29], v[12:13]
	v_mov_b64_e32 v[26:27], v[10:11]
	v_mov_b64_e32 v[24:25], v[8:9]
	v_mov_b64_e32 v[22:23], v[6:7]
	v_mov_b64_e32 v[20:21], v[4:5]
	v_mov_b64_e32 v[18:19], v[2:3]
	v_mov_b64_e32 v[16:17], v[0:1]
	v_mov_b64_e32 v[44:45], v[12:13]
	v_mov_b64_e32 v[42:43], v[10:11]
	v_mov_b64_e32 v[40:41], v[8:9]
	v_mov_b64_e32 v[38:39], v[6:7]
	v_mov_b64_e32 v[36:37], v[4:5]
	v_mov_b64_e32 v[34:35], v[2:3]
	v_mov_b64_e32 v[32:33], v[0:1]
	s_setprio 3
	s_branch .LBB0_323
